# grid barrier top level: XCD leaders poll the TOP counter itself (monotonic target) instead of a second TOPGEN word, last arriver skips the TOPGEN add; on top of convpipe+sched
# speedup vs baseline: 1.0041x; 1.0041x over previous
.LBB0_128:
	s_or_b64 exec, exec, s[18:19]
	v_cvt_f32_u32_e32 v3, v0
	s_waitcnt vmcnt(0)
	v_readfirstlane_b32 s18, v2
	s_add_u32 s14, s0, 0x7400
	s_addc_u32 s15, s1, 0
	v_rcp_iflag_f32_e32 v3, v3
	v_add_u32_e32 v1, s18, v1
	s_mov_b64 s[20:21], 0
	v_mul_f32_e32 v2, 0x4f7ffffe, v3
	v_cvt_u32_f32_e32 v2, v2
	v_sub_u32_e32 v3, 0, v0
	v_mul_lo_u32 v3, v3, v2
	v_mul_hi_u32 v3, v2, v3
	v_add_u32_e32 v2, v2, v3
	v_mul_hi_u32 v2, v1, v2
	v_mul_lo_u32 v3, v2, v0
	v_sub_u32_e32 v3, v1, v3
	v_add_u32_e32 v4, 1, v2
	v_cmp_ge_u32_e32 vcc, v3, v0
	v_add_u32_e32 v1, 1, v1
	s_nop 0
	v_cndmask_b32_e32 v2, v2, v4, vcc
	v_sub_u32_e32 v4, v3, v0
	v_cndmask_b32_e32 v3, v3, v4, vcc
	v_add_u32_e32 v4, 1, v2
	v_cmp_ge_u32_e32 vcc, v3, v0
	s_nop 1
	v_cndmask_b32_e32 v2, v2, v4, vcc
	v_mul_lo_u32 v3, v0, v2
	v_add_u32_e32 v0, v3, v0
	v_mov_b32_e32 v3, v0
	v_cmp_ne_u32_e32 vcc, v1, v0
	v_mov_b64_e32 v[0:1], s[14:15]
	s_and_saveexec_b64 s[18:19], vcc
	s_cbranch_execz .LBB0_140
	v_mov_b32_e32 v0, 0
	global_load_dword v1, v0, s[14:15] sc1
	s_mov_b64 s[22:23], 0
	s_waitcnt vmcnt(0)
	v_cmp_lt_u32_e32 vcc, v1, v3
	s_and_saveexec_b64 s[20:21], vcc
	s_cbranch_execz .LBB0_139
	s_mov_b32 s45, 1
	s_branch .LBB0_132

.LBB0_136:
	global_load_dword v1, v0, s[14:15] sc1
	s_add_i32 s45, s45, 1
	s_mov_b64 s[50:51], -1
	s_waitcnt vmcnt(0)
	v_cmp_ge_u32_e32 vcc, v1, v3
	s_orn2_b64 s[54:55], vcc, exec
	s_branch .LBB0_131

.LBB0_257:
	s_or_b64 exec, exec, s[6:7]
	v_cvt_f32_u32_e32 v3, v0
	s_waitcnt vmcnt(0)
	v_readfirstlane_b32 s2, v2
	s_mov_b64 s[6:7], 0
	v_rcp_iflag_f32_e32 v3, v3
	v_add_u32_e32 v1, s2, v1
	v_add_u32_e32 v4, 1, v1
	v_readlane_b32 s2, v253, 23
	v_mul_f32_e32 v2, 0x4f7ffffe, v3
	v_cvt_u32_f32_e32 v2, v2
	v_sub_u32_e32 v3, 0, v0
	v_readlane_b32 s3, v253, 24
	v_mul_lo_u32 v3, v3, v2
	v_mul_hi_u32 v3, v2, v3
	v_add_u32_e32 v2, v2, v3
	v_mul_hi_u32 v2, v1, v2
	v_mul_lo_u32 v3, v2, v0
	v_sub_u32_e32 v1, v1, v3
	v_add_u32_e32 v5, 1, v2
	v_cmp_ge_u32_e32 vcc, v1, v0
	v_sub_u32_e32 v3, v1, v0
	s_nop 0
	v_cndmask_b32_e32 v2, v2, v5, vcc
	v_cndmask_b32_e32 v1, v1, v3, vcc
	v_add_u32_e32 v3, 1, v2
	v_cmp_ge_u32_e32 vcc, v1, v0
	s_nop 1
	v_cndmask_b32_e32 v2, v2, v3, vcc
	v_mul_lo_u32 v1, v0, v2
	v_add_u32_e32 v0, v1, v0
	v_mov_b32_e32 v3, v0
	v_cmp_ne_u32_e32 vcc, v4, v0
	v_mov_b64_e32 v[0:1], s[2:3]
	s_and_saveexec_b64 s[4:5], vcc
	s_cbranch_execz .LBB0_269
	v_readlane_b32 s2, v253, 21
	v_mov_b32_e32 v0, 0
	v_readlane_b32 s3, v253, 22
	s_mov_b64 s[10:11], 0
	s_nop 3
	global_load_dword v1, v0, s[2:3] sc1
	s_waitcnt vmcnt(0)
	v_cmp_lt_u32_e32 vcc, v1, v3
	s_and_saveexec_b64 s[6:7], vcc
	s_cbranch_execz .LBB0_268
	s_mov_b32 s2, 1
	s_branch .LBB0_261

.LBB0_265:
	v_readlane_b32 s14, v253, 21
	v_readlane_b32 s15, v253, 22
	s_add_i32 s2, s2, 1
	s_nop 3
	global_load_dword v1, v0, s[14:15] sc1
	s_mov_b64 s[14:15], -1
	s_waitcnt vmcnt(0)
	v_cmp_ge_u32_e32 vcc, v1, v3
	s_orn2_b64 s[18:19], vcc, exec
	s_branch .LBB0_260

.LBB0_373:
	s_or_b64 exec, exec, s[22:23]
	v_cvt_f32_u32_e32 v3, v0
	s_waitcnt vmcnt(0)
	v_readfirstlane_b32 s6, v2
	s_mov_b64 s[22:23], 0
	v_rcp_iflag_f32_e32 v3, v3
	v_add_u32_e32 v1, s6, v1
	v_add_u32_e32 v4, 1, v1
	v_readlane_b32 s6, v253, 23
	v_mul_f32_e32 v2, 0x4f7ffffe, v3
	v_cvt_u32_f32_e32 v2, v2
	v_sub_u32_e32 v3, 0, v0
	v_readlane_b32 s7, v253, 24
	v_mul_lo_u32 v3, v3, v2
	v_mul_hi_u32 v3, v2, v3
	v_add_u32_e32 v2, v2, v3
	v_mul_hi_u32 v2, v1, v2
	v_mul_lo_u32 v3, v2, v0
	v_sub_u32_e32 v1, v1, v3
	v_add_u32_e32 v5, 1, v2
	v_cmp_ge_u32_e32 vcc, v1, v0
	v_sub_u32_e32 v3, v1, v0
	s_nop 0
	v_cndmask_b32_e32 v2, v2, v5, vcc
	v_cndmask_b32_e32 v1, v1, v3, vcc
	v_add_u32_e32 v3, 1, v2
	v_cmp_ge_u32_e32 vcc, v1, v0
	s_nop 1
	v_cndmask_b32_e32 v2, v2, v3, vcc
	v_mul_lo_u32 v1, v0, v2
	v_add_u32_e32 v0, v1, v0
	v_mov_b32_e32 v3, v0
	v_cmp_ne_u32_e32 vcc, v4, v0
	v_mov_b64_e32 v[0:1], s[6:7]
	s_and_saveexec_b64 s[6:7], vcc
	s_cbranch_execz .LBB0_385
	v_readlane_b32 s22, v253, 21
	v_readlane_b32 s23, v253, 22
	s_mov_b64 s[24:25], 0
	s_nop 3
	global_load_dword v0, v149, s[22:23] sc1
	s_waitcnt vmcnt(0)
	v_cmp_lt_u32_e32 vcc, v0, v3
	s_and_saveexec_b64 s[22:23], vcc
	s_cbranch_execz .LBB0_384
	s_mov_b32 s33, 1
	s_branch .LBB0_377

.LBB0_381:
	v_readlane_b32 s28, v253, 21
	v_readlane_b32 s29, v253, 22
	s_add_i32 s33, s33, 1
	s_mov_b64 s[30:31], -1
	s_nop 2
	global_load_dword v0, v149, s[28:29] sc1
	s_waitcnt vmcnt(0)
	v_cmp_ge_u32_e32 vcc, v0, v3
	s_orn2_b64 s[28:29], vcc, exec
	s_branch .LBB0_376

.LBB0_706:
	s_or_b64 exec, exec, s[22:23]
	s_waitcnt vmcnt(0)
	v_readfirstlane_b32 s6, v2
	v_cvt_f32_u32_e32 v2, v0
	v_sub_u32_e32 v3, 0, v0
	v_add_u32_e32 v1, s6, v1
	v_readlane_b32 s6, v253, 23
	v_rcp_iflag_f32_e32 v2, v2
	v_readlane_b32 s7, v253, 24
	s_mov_b64 s[22:23], 0
	v_mul_f32_e32 v2, 0x4f7ffffe, v2
	v_cvt_u32_f32_e32 v2, v2
	v_mul_lo_u32 v3, v3, v2
	v_mul_hi_u32 v3, v2, v3
	v_add_u32_e32 v2, v2, v3
	v_mul_hi_u32 v2, v1, v2
	v_mul_lo_u32 v3, v2, v0
	v_sub_u32_e32 v3, v1, v3
	v_cmp_ge_u32_e32 vcc, v3, v0
	v_add_u32_e32 v4, 1, v2
	v_add_u32_e32 v1, 1, v1
	v_cndmask_b32_e32 v2, v2, v4, vcc
	v_sub_u32_e32 v4, v3, v0
	v_cndmask_b32_e32 v3, v3, v4, vcc
	v_cmp_ge_u32_e32 vcc, v3, v0
	v_add_u32_e32 v3, 1, v2
	s_nop 0
	v_cndmask_b32_e32 v2, v2, v3, vcc
	v_mul_lo_u32 v3, v0, v2
	v_add_u32_e32 v0, v3, v0
	v_mov_b32_e32 v3, v0
	v_cmp_ne_u32_e32 vcc, v1, v0
	v_mov_b64_e32 v[0:1], s[6:7]
	s_and_saveexec_b64 s[6:7], vcc
	s_cbranch_execz .LBB0_718
	v_readlane_b32 s22, v253, 21
	v_readlane_b32 s23, v253, 22
	s_mov_b64 s[24:25], 0
	s_nop 3
	global_load_dword v0, v149, s[22:23] sc1
	s_waitcnt vmcnt(0)
	v_cmp_lt_u32_e32 vcc, v0, v3
	s_and_saveexec_b64 s[22:23], vcc
	s_cbranch_execz .LBB0_717
	s_mov_b32 s33, 1
	s_branch .LBB0_710
